# hoisted second prologue k-tile loads above the first barrier (projA, G, resid1/2) and moved the grid-barrier leader L1 invalidate after its XGEN release
# baseline (speedup 1.0000x reference)
; DEV unsigned xb_add(unsigned* p, unsigned v) { return __hip_atomic_fetch_add(p, v, __ATOMIC_RELAXED, __HIP_MEMORY_SCOPE_AGENT); }
; DEV void xcd_barrier(const XcdBarrier& b) {
;     ...
;       __builtin_amdgcn_fence(__ATOMIC_ACQUIRE, "agent");
;       xb_add(&bar[XB_XGEN(b.x)], 1u);
;       asm volatile("s_waitcnt vmcnt(0)" ::: "memory");
.LBB0_104:
	s_or_b64 exec, exec, s[4:5]
	s_mov_b64 s[4:5], exec
	v_mbcnt_lo_u32_b32 v0, s4, 0
	v_mbcnt_hi_u32_b32 v0, s5, v0
	v_cmp_eq_u32_e32 vcc, 0, v0
	s_waitcnt vmcnt(0)
	s_and_saveexec_b64 s[6:7], vcc
	s_cbranch_execz .LBB0_106
	s_bcnt1_i32_b64 s4, s[4:5]
	v_mov_b32_e32 v0, 0x2000
	v_mov_b32_e32 v1, s4
	global_atomic_add v0, v1, s[2:3] offset:1024
.LBB0_106:
	s_or_b64 exec, exec, s[6:7]
	buffer_inv sc1
	s_waitcnt vmcnt(0)

; DEV unsigned xb_add(unsigned* p, unsigned v) { return __hip_atomic_fetch_add(p, v, __ATOMIC_RELAXED, __HIP_MEMORY_SCOPE_AGENT); }
; DEV void xcd_barrier(const XcdBarrier& b) {
;     ...
;       __builtin_amdgcn_fence(__ATOMIC_ACQUIRE, "agent");
;       xb_add(&bar[XB_XGEN(b.x)], 1u);
;       asm volatile("s_waitcnt vmcnt(0)" ::: "memory");
.LBB0_180:
	s_or_b64 exec, exec, s[2:3]
	s_mov_b64 s[2:3], exec
	v_mbcnt_lo_u32_b32 v0, s2, 0
	v_mbcnt_hi_u32_b32 v0, s3, v0
	v_cmp_eq_u32_e32 vcc, 0, v0
	s_waitcnt vmcnt(0)
	s_and_saveexec_b64 s[8:9], vcc
	s_cbranch_execz .LBB0_182
	s_bcnt1_i32_b64 s2, s[2:3]
	v_mov_b32_e32 v0, s2
	v_mov_b32_e32 v2, 0x2000
	global_atomic_add v2, v0, s[6:7] offset:1024
.LBB0_182:
	s_or_b64 exec, exec, s[8:9]
	buffer_inv sc1
	s_waitcnt vmcnt(0)

; template <int BN, bool TRANS = false>
; DEV void gemm256_acc(f32x4 (&acc)[4][BN / 32], const bf16_t* __restrict__ A, int lda, int m_valid,
;                      const bf16_t* __restrict__ Bt, int ldb, int K, bf16_t* lds) {
;     ...
;   const bf16_t* ga0 = A + (size_t)min(crow, m_valid - 1) * lda + ckc;
;   const bf16_t* ga1 = A + (size_t)min(crow + 64, m_valid - 1) * lda + ckc;
;   const bf16_t* ga2 = A + (size_t)min(crow + 128, m_valid - 1) * lda + ckc;
;   const bf16_t* ga3 = A + (size_t)min(crow + 192, m_valid - 1) * lda + ckc;
;   const bf16_t* gb = Bt + (size_t)crow * ldb + ckc;
;   u32x4 ra0, ra1, ra2, ra3, rb0, rb1, rb2, rb3;
;     ...
;   const int nk = K / 64;
;   const int aoff = (wm * 64 + lr) * LS;
;   const int boff = (wn * (BN / 2) + lr) * LS;
;   GLOAD(0)
;   __syncthreads();
.LBB0_221:
	s_andn2_b64 vcc, exec, s[2:3]
	s_cbranch_vccnz .LBB0_228
	s_waitcnt vmcnt(2)
	v_mov_b32_e32 v42, v181
	s_mov_b32 s0, 0x40000
	v_ashrrev_i32_e32 v34, 3, v42
	v_min_i32_e32 v2, 0xff, v34
	v_ashrrev_i32_e32 v3, 31, v2
	v_lshlrev_b64 v[2:3], 11, v[2:3]
	v_lshlrev_b32_e32 v0, 4, v42
	v_lshl_add_u64 v[2:3], s[18:19], 0, v[2:3]
	v_and_b32_e32 v0, 0x70, v0
	v_add_u32_e32 v43, 64, v34
	v_lshl_add_u64 v[162:163], v[2:3], 0, v[0:1]
	v_min_i32_e32 v2, 0xff, v43
	v_ashrrev_i32_e32 v3, 31, v2
	v_lshlrev_b64 v[2:3], 11, v[2:3]
	v_lshl_add_u64 v[2:3], s[18:19], 0, v[2:3]
	v_add_u32_e32 v44, 0x80, v34
	v_lshl_add_u64 v[164:165], v[2:3], 0, v[0:1]
	v_min_i32_e32 v2, 0xff, v44
	v_ashrrev_i32_e32 v3, 31, v2
	v_lshlrev_b64 v[2:3], 11, v[2:3]
	v_lshl_add_u64 v[2:3], s[18:19], 0, v[2:3]
	v_add_u32_e32 v45, 0xc0, v34
	v_lshl_add_u64 v[166:167], v[2:3], 0, v[0:1]
	v_min_i32_e32 v2, 0xff, v45
	v_ashrrev_i32_e32 v3, 31, v2
	v_lshlrev_b64 v[2:3], 11, v[2:3]
	v_lshl_add_u64 v[2:3], s[18:19], 0, v[2:3]
	v_ashrrev_i32_e32 v35, 31, v34
	v_lshl_add_u64 v[168:169], v[2:3], 0, v[0:1]
	v_lshlrev_b64 v[2:3], 11, v[34:35]
	v_lshl_add_u64 v[2:3], s[16:17], 0, v[2:3]
	v_lshl_add_u64 v[170:171], v[2:3], 0, v[0:1]
	v_add_co_u32_e32 v36, vcc, s63, v170
	global_load_dwordx4 v[2:5], v[162:163], off
	global_load_dwordx4 v[6:9], v[164:165], off
	global_load_dwordx4 v[10:13], v[166:167], off
	global_load_dwordx4 v[14:17], v[168:169], off
	v_addc_co_u32_e32 v37, vcc, 0, v171, vcc
	v_add_co_u32_e32 v38, vcc, s0, v170
	s_mov_b32 s0, 0x60000
	s_nop 0
	v_addc_co_u32_e32 v39, vcc, 0, v171, vcc
	global_load_dwordx4 v[18:21], v[170:171], off
	global_load_dwordx4 v[22:25], v[36:37], off
	v_add_co_u32_e32 v40, vcc, s0, v170
	global_load_dwordx4 v[26:29], v[38:39], off
	s_nop 0
	v_addc_co_u32_e32 v41, vcc, 0, v171, vcc
	global_load_dwordx4 v[30:33], v[40:41], off
	global_load_dwordx4 v[130:133], v[162:163], off offset:128
	global_load_dwordx4 v[134:137], v[164:165], off offset:128
	global_load_dwordx4 v[138:141], v[166:167], off offset:128
	global_load_dwordx4 v[142:145], v[168:169], off offset:128
	global_load_dwordx4 v[146:149], v[170:171], off offset:128
	global_load_dwordx4 v[150:153], v[36:37], off offset:128
	global_load_dwordx4 v[154:157], v[38:39], off offset:128
	global_load_dwordx4 v[158:161], v[40:41], off offset:128
	v_lshrrev_b32_e32 v35, 4, v42
	v_and_b32_e32 v0, 15, v42
	s_waitcnt vmcnt(17)
	v_lshrrev_b32_e32 v46, 1, v42
	v_bfe_u32 v47, v42, 1, 3
	v_lshlrev_b32_e32 v48, 1, v42
	v_xor_b32_e32 v42, v35, v42
	v_lshlrev_b32_e32 v42, 3, v42
	s_movk_i32 s1, 0x80
	v_and_b32_e32 v42, 56, v42
	v_bitop3_b32 v35, v35, v47, 3 bitop3:0x6c
	v_and_or_b32 v47, v48, s1, v0
	v_lshlrev_b32_e32 v48, 6, v34
	v_lshlrev_b32_e32 v34, 7, v34
	v_lshlrev_b32_e32 v178, 1, v42
	v_and_or_b32 v46, v46, s62, v0
	v_lshlrev_b32_e32 v0, 3, v35
	v_lshlrev_b32_e32 v35, 6, v43
	v_lshlrev_b32_e32 v43, 7, v43
	v_lshlrev_b32_e32 v49, 6, v44
	v_lshlrev_b32_e32 v44, 7, v44
	v_lshlrev_b32_e32 v50, 6, v45
	v_lshlrev_b32_e32 v45, 7, v45
	v_add3_u32 v42, 0, v34, v178
	v_add3_u32 v52, 0, v43, v178
	v_add3_u32 v53, 0, v44, v178
	v_add3_u32 v54, 0, v45, v178
	v_add3_u32 v34, s66, v34, v178
	s_barrier
; template <int BN, bool TRANS = false>
; DEV void gemm256_acc(f32x4 (&acc)[4][BN / 32], const bf16_t* __restrict__ A, int lda, int m_valid,
;                      const bf16_t* __restrict__ Bt, int ldb, int K, bf16_t* lds) {
;     ...
;   LSTORE(0)
;   GLOAD(64)
;   __syncthreads();
;   for (int kt = 0; kt < nk; kt++) {
;     const int cur = kt & 1;
;     gemm256_kstep<BN, TRANS>(acc, As + cur * A_SZ + aoff, Bs + cur * B_SZ + boff, sw0);
; DEV void phase_projA(const Params& p, int layer, int b, unsigned char* ldsraw) {
;     ...
; #pragma unroll
;     for (int i = 0; i < 4; i++)
; #pragma unroll
;       for (int j = 0; j < 8; j++) acc[i][j] = (f32x4){0.f, 0.f, 0.f, 0.f};
	s_mov_b64 s[2:3], 0x40000
	v_xor_b32_e32 v51, 32, v0
	v_lshl_add_u64 v[174:175], v[170:171], 0, s[2:3]
	s_mov_b64 s[2:3], 0x60000
	s_mov_b32 s0, 0
	v_lshl_add_u64 v[172:173], v[170:171], 0, s[84:85]
	v_lshl_add_u64 v[176:177], v[170:171], 0, s[2:3]
	v_lshl_add_u32 v179, v46, 7, 0
	v_lshl_add_u32 v182, v47, 7, s66
	v_lshlrev_b32_e32 v183, 1, v48
	v_lshlrev_b32_e32 v184, 1, v35
	v_lshlrev_b32_e32 v185, 1, v49
	v_lshlrev_b32_e32 v186, 1, v50
	v_lshlrev_b32_e32 v187, 1, v51
	s_mov_b32 s1, 0
	s_waitcnt vmcnt(15)
	ds_write_b128 v42, v[2:5]
	s_waitcnt vmcnt(14)
	ds_write_b128 v52, v[6:9]
	s_waitcnt vmcnt(13)
	ds_write_b128 v53, v[10:13]
	s_waitcnt vmcnt(12)
	ds_write_b128 v54, v[14:17]
	s_waitcnt vmcnt(11)
	ds_write_b128 v34, v[18:21]
	v_add3_u32 v2, s66, v43, v178
	s_waitcnt vmcnt(10)
	ds_write_b128 v2, v[22:25]
	v_add3_u32 v2, s66, v44, v178
	s_waitcnt vmcnt(9)
	ds_write_b128 v2, v[26:29]
	v_add3_u32 v2, s66, v45, v178
	s_waitcnt vmcnt(8)
	ds_write_b128 v2, v[30:33]
	v_mov_b32_e32 v2, 0
	v_mov_b32_e32 v3, v2
	v_mov_b32_e32 v4, v2
	v_mov_b32_e32 v5, v2
	v_mov_b32_e32 v6, v2
	v_mov_b32_e32 v7, v2
	v_mov_b32_e32 v8, v2
	v_mov_b32_e32 v9, v2
	v_mov_b32_e32 v14, v2
	v_mov_b32_e32 v15, v2
	v_mov_b32_e32 v16, v2
	v_mov_b32_e32 v17, v2
	v_mov_b32_e32 v22, v2
	v_mov_b32_e32 v23, v2
	v_mov_b32_e32 v24, v2
	v_mov_b32_e32 v25, v2
	v_mov_b32_e32 v10, v2
	v_mov_b32_e32 v11, v2
	v_mov_b32_e32 v12, v2
	v_mov_b32_e32 v13, v2
	v_mov_b32_e32 v18, v2
	v_mov_b32_e32 v19, v2
	v_mov_b32_e32 v20, v2
	v_mov_b32_e32 v21, v2
	v_mov_b32_e32 v26, v2
	v_mov_b32_e32 v27, v2
	v_mov_b32_e32 v28, v2
	v_mov_b32_e32 v29, v2
	v_mov_b32_e32 v30, v2
	v_mov_b32_e32 v31, v2
	v_mov_b32_e32 v32, v2
	v_mov_b32_e32 v33, v2
	v_mov_b32_e32 v34, v2
	v_mov_b32_e32 v35, v2
	v_mov_b32_e32 v36, v2
	v_mov_b32_e32 v37, v2
	v_mov_b32_e32 v38, v2
	v_mov_b32_e32 v39, v2
	v_mov_b32_e32 v40, v2
	v_mov_b32_e32 v41, v2
	v_mov_b32_e32 v46, v2
	v_mov_b32_e32 v47, v2
	v_mov_b32_e32 v48, v2
	v_mov_b32_e32 v49, v2
	v_mov_b32_e32 v54, v2
	v_mov_b32_e32 v55, v2
	v_mov_b32_e32 v56, v2
	v_mov_b32_e32 v57, v2
	v_mov_b32_e32 v42, v2
	v_mov_b32_e32 v43, v2
	v_mov_b32_e32 v44, v2
	v_mov_b32_e32 v45, v2
	v_mov_b32_e32 v50, v2
	v_mov_b32_e32 v51, v2
	v_mov_b32_e32 v52, v2
	v_mov_b32_e32 v53, v2
	v_mov_b32_e32 v58, v2
	v_mov_b32_e32 v59, v2
	v_mov_b32_e32 v60, v2
	v_mov_b32_e32 v61, v2
	v_mov_b32_e32 v62, v2
	v_mov_b32_e32 v63, v2
	v_mov_b32_e32 v64, v2
	v_mov_b32_e32 v65, v2
	v_mov_b32_e32 v66, v2
	v_mov_b32_e32 v67, v2
	v_mov_b32_e32 v68, v2
	v_mov_b32_e32 v69, v2
	v_mov_b32_e32 v70, v2
	v_mov_b32_e32 v71, v2
	v_mov_b32_e32 v72, v2
	v_mov_b32_e32 v73, v2
	v_mov_b32_e32 v78, v2
	v_mov_b32_e32 v79, v2
	v_mov_b32_e32 v80, v2
	v_mov_b32_e32 v81, v2
	v_mov_b32_e32 v86, v2
	v_mov_b32_e32 v87, v2
	v_mov_b32_e32 v88, v2
	v_mov_b32_e32 v89, v2
	v_mov_b32_e32 v74, v2
	v_mov_b32_e32 v75, v2
	v_mov_b32_e32 v76, v2
	v_mov_b32_e32 v77, v2
	v_mov_b32_e32 v82, v2
	v_mov_b32_e32 v83, v2
	v_mov_b32_e32 v84, v2
	v_mov_b32_e32 v85, v2
	v_mov_b32_e32 v90, v2
	v_mov_b32_e32 v91, v2
	v_mov_b32_e32 v92, v2
	v_mov_b32_e32 v93, v2
	v_mov_b32_e32 v94, v2
	v_mov_b32_e32 v95, v2
	v_mov_b32_e32 v96, v2
	v_mov_b32_e32 v97, v2
	v_mov_b32_e32 v98, v2
	v_mov_b32_e32 v99, v2
	v_mov_b32_e32 v100, v2
	v_mov_b32_e32 v101, v2
	v_mov_b32_e32 v106, v2
	v_mov_b32_e32 v107, v2
	v_mov_b32_e32 v108, v2
	v_mov_b32_e32 v109, v2
	v_mov_b32_e32 v114, v2
	v_mov_b32_e32 v115, v2
	v_mov_b32_e32 v116, v2
	v_mov_b32_e32 v117, v2
	v_mov_b32_e32 v118, v2
	v_mov_b32_e32 v119, v2
	v_mov_b32_e32 v120, v2
	v_mov_b32_e32 v121, v2
	v_mov_b32_e32 v102, v2
	v_mov_b32_e32 v103, v2
	v_mov_b32_e32 v104, v2
	v_mov_b32_e32 v105, v2
	v_mov_b32_e32 v110, v2
	v_mov_b32_e32 v111, v2
	v_mov_b32_e32 v112, v2
	v_mov_b32_e32 v113, v2
	v_mov_b32_e32 v122, v2
	v_mov_b32_e32 v123, v2
	v_mov_b32_e32 v124, v2
	v_mov_b32_e32 v125, v2
	v_mov_b32_e32 v126, v2
	v_mov_b32_e32 v127, v2
	v_mov_b32_e32 v128, v2
	v_mov_b32_e32 v129, v2
	s_waitcnt lgkmcnt(0)
	s_barrier
	v_lshlrev_b32_e32 v211, 1, v0
	v_add_u32_e32 v216, v179, v211
	v_add_u32_e32 v206, v182, v211
	ds_read_b128 v[188:191], v216
	ds_read_b128 v[192:195], v216 offset:2048
	ds_read_b128 v[196:199], v216 offset:4096
	ds_read_b128 v[200:203], v216 offset:6144
	ds_read_b128 v[236:239], v206
	ds_read_b128 v[240:243], v206 offset:2048
	ds_read_b128 v[244:247], v206 offset:4096
	ds_read_b128 v[248:251], v206 offset:6144

; template <int BN, bool TRANS = false>
; DEV void gemm256_acc(f32x4 (&acc)[4][BN / 32], const bf16_t* __restrict__ A, int lda, int m_valid,
;                      const bf16_t* __restrict__ Bt, int ldb, int K, bf16_t* lds) {
;     ...
;   const bf16_t* ga0 = A + (size_t)min(crow, m_valid - 1) * lda + ckc;
;   const bf16_t* ga1 = A + (size_t)min(crow + 64, m_valid - 1) * lda + ckc;
;   const bf16_t* ga2 = A + (size_t)min(crow + 128, m_valid - 1) * lda + ckc;
;   const bf16_t* ga3 = A + (size_t)min(crow + 192, m_valid - 1) * lda + ckc;
;   const bf16_t* gb = Bt + (size_t)crow * ldb + ckc;
;   u32x4 ra0, ra1, ra2, ra3, rb0, rb1, rb2, rb3;
;     ...
;   const int nk = K / 64;
;   const int aoff = (wm * 64 + lr) * LS;
;   const int boff = (wn * (BN / 2) + lr) * LS;
;   GLOAD(0)
;   __syncthreads();
.LBB0_306:
	s_waitcnt vmcnt(2)
	v_mov_b32_e32 v42, v181
	s_mov_b32 s0, 0x40000
	v_ashrrev_i32_e32 v34, 3, v42
	v_min_i32_e32 v2, 0xff, v34
	v_ashrrev_i32_e32 v3, 31, v2
	v_lshlrev_b64 v[2:3], 11, v[2:3]
	v_lshlrev_b32_e32 v0, 4, v42
	v_lshl_add_u64 v[2:3], s[18:19], 0, v[2:3]
	v_and_b32_e32 v0, 0x70, v0
	v_add_u32_e32 v43, 64, v34
	v_lshl_add_u64 v[162:163], v[2:3], 0, v[0:1]
	v_min_i32_e32 v2, 0xff, v43
	v_ashrrev_i32_e32 v3, 31, v2
	v_lshlrev_b64 v[2:3], 11, v[2:3]
	v_lshl_add_u64 v[2:3], s[18:19], 0, v[2:3]
	v_add_u32_e32 v44, 0x80, v34
	v_lshl_add_u64 v[164:165], v[2:3], 0, v[0:1]
	v_min_i32_e32 v2, 0xff, v44
	v_ashrrev_i32_e32 v3, 31, v2
	v_lshlrev_b64 v[2:3], 11, v[2:3]
	v_lshl_add_u64 v[2:3], s[18:19], 0, v[2:3]
	v_add_u32_e32 v45, 0xc0, v34
	v_lshl_add_u64 v[166:167], v[2:3], 0, v[0:1]
	v_min_i32_e32 v2, 0xff, v45
	v_ashrrev_i32_e32 v3, 31, v2
	v_lshlrev_b64 v[2:3], 11, v[2:3]
	v_lshl_add_u64 v[2:3], s[18:19], 0, v[2:3]
	v_ashrrev_i32_e32 v35, 31, v34
	v_lshl_add_u64 v[168:169], v[2:3], 0, v[0:1]
	v_lshlrev_b64 v[2:3], 11, v[34:35]
	v_lshl_add_u64 v[2:3], s[16:17], 0, v[2:3]
	v_lshl_add_u64 v[170:171], v[2:3], 0, v[0:1]
	v_add_co_u32_e32 v36, vcc, s63, v170
	global_load_dwordx4 v[2:5], v[162:163], off
	global_load_dwordx4 v[6:9], v[164:165], off
	global_load_dwordx4 v[10:13], v[166:167], off
	global_load_dwordx4 v[14:17], v[168:169], off
	v_addc_co_u32_e32 v37, vcc, 0, v171, vcc
	v_add_co_u32_e32 v38, vcc, s0, v170
	s_mov_b32 s0, 0x60000
	s_nop 0
	v_addc_co_u32_e32 v39, vcc, 0, v171, vcc
	global_load_dwordx4 v[18:21], v[170:171], off
	global_load_dwordx4 v[22:25], v[36:37], off
	v_add_co_u32_e32 v40, vcc, s0, v170
	global_load_dwordx4 v[26:29], v[38:39], off
	s_nop 0
	v_addc_co_u32_e32 v41, vcc, 0, v171, vcc
	global_load_dwordx4 v[30:33], v[40:41], off
	global_load_dwordx4 v[130:133], v[162:163], off offset:128
	global_load_dwordx4 v[134:137], v[164:165], off offset:128
	global_load_dwordx4 v[138:141], v[166:167], off offset:128
	global_load_dwordx4 v[142:145], v[168:169], off offset:128
	global_load_dwordx4 v[146:149], v[170:171], off offset:128
	global_load_dwordx4 v[150:153], v[36:37], off offset:128
	global_load_dwordx4 v[154:157], v[38:39], off offset:128
	global_load_dwordx4 v[158:161], v[40:41], off offset:128
	v_lshrrev_b32_e32 v35, 4, v42
	v_and_b32_e32 v0, 15, v42
	s_waitcnt vmcnt(17)
	v_lshrrev_b32_e32 v46, 1, v42
	v_bfe_u32 v47, v42, 1, 3
	v_lshlrev_b32_e32 v48, 1, v42
	v_xor_b32_e32 v42, v35, v42
	v_lshlrev_b32_e32 v42, 3, v42
	s_movk_i32 s1, 0x80
	v_and_b32_e32 v42, 56, v42
	v_bitop3_b32 v35, v35, v47, 3 bitop3:0x6c
	v_and_or_b32 v47, v48, s1, v0
	v_lshlrev_b32_e32 v48, 6, v34
	v_lshlrev_b32_e32 v34, 7, v34
	v_lshlrev_b32_e32 v178, 1, v42
	v_and_or_b32 v46, v46, s62, v0
	v_lshlrev_b32_e32 v0, 3, v35
	v_lshlrev_b32_e32 v35, 6, v43
	v_lshlrev_b32_e32 v43, 7, v43
	v_lshlrev_b32_e32 v49, 6, v44
	v_lshlrev_b32_e32 v44, 7, v44
	v_lshlrev_b32_e32 v50, 6, v45
	v_lshlrev_b32_e32 v45, 7, v45
	v_add3_u32 v42, 0, v34, v178
	v_add3_u32 v34, s66, v34, v178
	v_add3_u32 v52, 0, v43, v178
	v_add3_u32 v53, 0, v44, v178
	v_add3_u32 v54, 0, v45, v178
	v_add3_u32 v43, s66, v43, v178
	s_barrier
; template <int BN, bool TRANS = false>
; DEV void gemm256_acc(f32x4 (&acc)[4][BN / 32], const bf16_t* __restrict__ A, int lda, int m_valid,
;                      const bf16_t* __restrict__ Bt, int ldb, int K, bf16_t* lds) {
;     ...
;   LSTORE(0)
;   GLOAD(64)
;   __syncthreads();
;   for (int kt = 0; kt < nk; kt++) {
;     const int cur = kt & 1;
;     gemm256_kstep<BN, TRANS>(acc, As + cur * A_SZ + aoff, Bs + cur * B_SZ + boff, sw0);
; DEV void phase_projA(const Params& p, int layer, int b, unsigned char* ldsraw) {
;     ...
; #pragma unroll
;     for (int i = 0; i < 4; i++)
; #pragma unroll
;       for (int j = 0; j < 8; j++) acc[i][j] = (f32x4){0.f, 0.f, 0.f, 0.f};
	s_mov_b64 s[2:3], 0x40000
	v_xor_b32_e32 v51, 32, v0
	v_lshl_add_u64 v[174:175], v[170:171], 0, s[2:3]
	s_mov_b64 s[2:3], 0x60000
	s_mov_b32 s0, 0
	v_lshl_add_u32 v179, v46, 7, 0
	v_lshl_add_u32 v182, v47, 7, s66
	v_lshlrev_b32_e32 v183, 1, v48
	v_lshlrev_b32_e32 v184, 1, v35
	v_lshlrev_b32_e32 v185, 1, v49
	v_lshlrev_b32_e32 v186, 1, v50
	v_lshlrev_b32_e32 v187, 1, v51
	s_mov_b32 s1, 0
	v_lshl_add_u64 v[172:173], v[170:171], 0, s[84:85]
	v_lshl_add_u64 v[176:177], v[170:171], 0, s[2:3]
	s_waitcnt vmcnt(11)
	ds_write_b128 v34, v[18:21]
	ds_write_b128 v42, v[2:5]
	s_waitcnt vmcnt(10)
	ds_write_b128 v43, v[22:25]
	ds_write_b128 v52, v[6:9]
	ds_write_b128 v53, v[10:13]
	ds_write_b128 v54, v[14:17]
	v_add3_u32 v2, s66, v44, v178
	s_waitcnt vmcnt(9)
	ds_write_b128 v2, v[26:29]
	v_add3_u32 v2, s66, v45, v178
	s_waitcnt vmcnt(8)
	ds_write_b128 v2, v[30:33]
	v_mov_b32_e32 v2, 0
	v_mov_b32_e32 v3, v2
	v_mov_b32_e32 v4, v2
	v_mov_b32_e32 v5, v2
	v_mov_b32_e32 v10, v2
	v_mov_b32_e32 v11, v2
	v_mov_b32_e32 v12, v2
	v_mov_b32_e32 v13, v2
	v_mov_b32_e32 v18, v2
	v_mov_b32_e32 v19, v2
	v_mov_b32_e32 v20, v2
	v_mov_b32_e32 v21, v2
	v_mov_b32_e32 v26, v2
	v_mov_b32_e32 v27, v2
	v_mov_b32_e32 v28, v2
	v_mov_b32_e32 v29, v2
	v_mov_b32_e32 v6, v2
	v_mov_b32_e32 v7, v2
	v_mov_b32_e32 v8, v2
	v_mov_b32_e32 v9, v2
	v_mov_b32_e32 v14, v2
	v_mov_b32_e32 v15, v2
	v_mov_b32_e32 v16, v2
	v_mov_b32_e32 v17, v2
	v_mov_b32_e32 v22, v2
	v_mov_b32_e32 v23, v2
	v_mov_b32_e32 v24, v2
	v_mov_b32_e32 v25, v2
	v_mov_b32_e32 v30, v2
	v_mov_b32_e32 v31, v2
	v_mov_b32_e32 v32, v2
	v_mov_b32_e32 v33, v2
	v_mov_b32_e32 v34, v2
	v_mov_b32_e32 v35, v2
	v_mov_b32_e32 v36, v2
	v_mov_b32_e32 v37, v2
	v_mov_b32_e32 v42, v2
	v_mov_b32_e32 v43, v2
	v_mov_b32_e32 v44, v2
	v_mov_b32_e32 v45, v2
	v_mov_b32_e32 v50, v2
	v_mov_b32_e32 v51, v2
	v_mov_b32_e32 v52, v2
	v_mov_b32_e32 v53, v2
	v_mov_b32_e32 v58, v2
	v_mov_b32_e32 v59, v2
	v_mov_b32_e32 v60, v2
	v_mov_b32_e32 v61, v2
	v_mov_b32_e32 v38, v2
	v_mov_b32_e32 v39, v2
	v_mov_b32_e32 v40, v2
	v_mov_b32_e32 v41, v2
	v_mov_b32_e32 v46, v2
	v_mov_b32_e32 v47, v2
	v_mov_b32_e32 v48, v2
	v_mov_b32_e32 v49, v2
	v_mov_b32_e32 v54, v2
	v_mov_b32_e32 v55, v2
	v_mov_b32_e32 v56, v2
	v_mov_b32_e32 v57, v2
	v_mov_b32_e32 v62, v2
	v_mov_b32_e32 v63, v2
	v_mov_b32_e32 v64, v2
	v_mov_b32_e32 v65, v2
	v_mov_b32_e32 v66, v2
	v_mov_b32_e32 v67, v2
	v_mov_b32_e32 v68, v2
	v_mov_b32_e32 v69, v2
	v_mov_b32_e32 v74, v2
	v_mov_b32_e32 v75, v2
	v_mov_b32_e32 v76, v2
	v_mov_b32_e32 v77, v2
	v_mov_b32_e32 v82, v2
	v_mov_b32_e32 v83, v2
	v_mov_b32_e32 v84, v2
	v_mov_b32_e32 v85, v2
	v_mov_b32_e32 v90, v2
	v_mov_b32_e32 v91, v2
	v_mov_b32_e32 v92, v2
	v_mov_b32_e32 v93, v2
	v_mov_b32_e32 v70, v2
	v_mov_b32_e32 v71, v2
	v_mov_b32_e32 v72, v2
	v_mov_b32_e32 v73, v2
	v_mov_b32_e32 v78, v2
	v_mov_b32_e32 v79, v2
	v_mov_b32_e32 v80, v2
	v_mov_b32_e32 v81, v2
	v_mov_b32_e32 v86, v2
	v_mov_b32_e32 v87, v2
	v_mov_b32_e32 v88, v2
	v_mov_b32_e32 v89, v2
	v_mov_b32_e32 v94, v2
	v_mov_b32_e32 v95, v2
	v_mov_b32_e32 v96, v2
	v_mov_b32_e32 v97, v2
	v_mov_b32_e32 v98, v2
	v_mov_b32_e32 v99, v2
	v_mov_b32_e32 v100, v2
	v_mov_b32_e32 v101, v2
	v_mov_b32_e32 v106, v2
	v_mov_b32_e32 v107, v2
	v_mov_b32_e32 v108, v2
	v_mov_b32_e32 v109, v2
	v_mov_b32_e32 v114, v2
	v_mov_b32_e32 v115, v2
	v_mov_b32_e32 v116, v2
	v_mov_b32_e32 v117, v2
	v_mov_b32_e32 v122, v2
	v_mov_b32_e32 v123, v2
	v_mov_b32_e32 v124, v2
	v_mov_b32_e32 v125, v2
	v_mov_b32_e32 v102, v2
	v_mov_b32_e32 v103, v2
	v_mov_b32_e32 v104, v2
	v_mov_b32_e32 v105, v2
	v_mov_b32_e32 v110, v2
	v_mov_b32_e32 v111, v2
	v_mov_b32_e32 v112, v2
	v_mov_b32_e32 v113, v2
	v_mov_b32_e32 v118, v2
	v_mov_b32_e32 v119, v2
	v_mov_b32_e32 v120, v2
	v_mov_b32_e32 v121, v2
	v_mov_b32_e32 v126, v2
	v_mov_b32_e32 v127, v2
	v_mov_b32_e32 v128, v2
	v_mov_b32_e32 v129, v2
	s_waitcnt lgkmcnt(0)
	s_barrier
	v_lshlrev_b32_e32 v211, 1, v0
	v_add_u32_e32 v216, v179, v211
	v_add_u32_e32 v206, v182, v211
	ds_read_b128 v[188:191], v216
	ds_read_b128 v[192:195], v216 offset:2048
	ds_read_b128 v[196:199], v216 offset:4096
	ds_read_b128 v[200:203], v216 offset:6144
	ds_read_b128 v[236:239], v206
	ds_read_b128 v[240:243], v206 offset:2048
	ds_read_b128 v[244:247], v206 offset:4096
	ds_read_b128 v[248:251], v206 offset:6144

; DEV unsigned xb_add(unsigned* p, unsigned v) { return __hip_atomic_fetch_add(p, v, __ATOMIC_RELAXED, __HIP_MEMORY_SCOPE_AGENT); }
; DEV void xcd_barrier(const XcdBarrier& b) {
;     ...
;       __builtin_amdgcn_fence(__ATOMIC_ACQUIRE, "agent");
;       xb_add(&bar[XB_XGEN(b.x)], 1u);
;       asm volatile("s_waitcnt vmcnt(0)" ::: "memory");
.LBB0_516:
	s_or_b64 exec, exec, s[2:3]
	s_mov_b64 s[2:3], exec
	v_mbcnt_lo_u32_b32 v0, s2, 0
	v_mbcnt_hi_u32_b32 v0, s3, v0
	v_cmp_eq_u32_e32 vcc, 0, v0
	s_waitcnt vmcnt(0)
	s_and_saveexec_b64 s[6:7], vcc
	s_cbranch_execz .LBB0_518
	s_bcnt1_i32_b64 s2, s[2:3]
	v_mov_b32_e32 v0, s2
	v_mov_b32_e32 v2, 0x2000
	global_atomic_add v2, v0, s[4:5] offset:1024

; template <int BN, bool TRANS = false>
; DEV void gemm256_acc(f32x4 (&acc)[4][BN / 32], const bf16_t* __restrict__ A, int lda, int m_valid,
;                      const bf16_t* __restrict__ Bt, int ldb, int K, bf16_t* lds) {
;     ...
;   const bf16_t* ga0 = A + (size_t)min(crow, m_valid - 1) * lda + ckc;
;   const bf16_t* ga1 = A + (size_t)min(crow + 64, m_valid - 1) * lda + ckc;
;   const bf16_t* ga2 = A + (size_t)min(crow + 128, m_valid - 1) * lda + ckc;
;   const bf16_t* ga3 = A + (size_t)min(crow + 192, m_valid - 1) * lda + ckc;
;   const bf16_t* gb = Bt + (size_t)crow * ldb + ckc;
;   u32x4 ra0, ra1, ra2, ra3, rb0, rb1, rb2, rb3;
;     ...
;   const int nk = K / 64;
;   const int aoff = (wm * 64 + lr) * LS;
;   const int boff = (wn * (BN / 2) + lr) * LS;
;   GLOAD(0)
;   __syncthreads();
.LBB0_784:
	s_ashr_i32 s3, s2, 31
	s_xor_b64 s[8:9], s[8:9], -1
	s_lshl_b64 s[12:13], s[2:3], 19
	s_add_u32 s12, s88, s12
	s_addc_u32 s13, s89, s13
	s_ashr_i32 s11, s10, 31
	s_lshl_b32 s2, s2, 8
	s_lshl_b64 s[10:11], s[10:11], 11
	s_add_u32 s10, s92, s10
	v_mov_b32_e32 v42, v181
	s_addc_u32 s11, s93, s11
	s_sub_i32 s3, 0x207f, s2
	v_ashrrev_i32_e32 v34, 3, v42
	v_min_i32_e32 v2, s3, v34
	v_ashrrev_i32_e32 v3, 31, v2
	v_lshlrev_b64 v[2:3], 11, v[2:3]
	v_lshlrev_b32_e32 v0, 4, v42
	v_lshl_add_u64 v[2:3], s[12:13], 0, v[2:3]
	v_and_b32_e32 v0, 0x70, v0
	v_add_u32_e32 v43, 64, v34
	v_lshl_add_u64 v[162:163], v[2:3], 0, v[0:1]
	v_min_i32_e32 v2, s3, v43
	v_ashrrev_i32_e32 v3, 31, v2
	v_lshlrev_b64 v[2:3], 11, v[2:3]
	v_lshl_add_u64 v[2:3], s[12:13], 0, v[2:3]
	v_add_u32_e32 v44, 0x80, v34
	v_lshl_add_u64 v[164:165], v[2:3], 0, v[0:1]
	v_min_i32_e32 v2, s3, v44
	v_ashrrev_i32_e32 v3, 31, v2
	v_lshlrev_b64 v[2:3], 11, v[2:3]
	v_lshl_add_u64 v[2:3], s[12:13], 0, v[2:3]
	v_add_u32_e32 v45, 0xc0, v34
	v_lshl_add_u64 v[166:167], v[2:3], 0, v[0:1]
	v_min_i32_e32 v2, s3, v45
	v_ashrrev_i32_e32 v3, 31, v2
	v_lshlrev_b64 v[2:3], 11, v[2:3]
	v_lshl_add_u64 v[2:3], s[12:13], 0, v[2:3]
	v_ashrrev_i32_e32 v35, 31, v34
	v_lshl_add_u64 v[168:169], v[2:3], 0, v[0:1]
	v_lshlrev_b64 v[2:3], 11, v[34:35]
	v_lshl_add_u64 v[2:3], s[10:11], 0, v[2:3]
	v_lshl_add_u64 v[170:171], v[2:3], 0, v[0:1]
	v_add_co_u32_e32 v36, vcc, s63, v170
	s_mov_b32 s3, 0x40000
	s_nop 0
	v_addc_co_u32_e32 v37, vcc, 0, v171, vcc
	v_add_co_u32_e32 v38, vcc, s3, v170
	s_mov_b32 s3, 0x60000
	s_nop 0
	v_addc_co_u32_e32 v39, vcc, 0, v171, vcc
	global_load_dwordx4 v[2:5], v[162:163], off
	global_load_dwordx4 v[6:9], v[164:165], off
	global_load_dwordx4 v[10:13], v[166:167], off
	global_load_dwordx4 v[14:17], v[168:169], off
	v_add_co_u32_e32 v40, vcc, s3, v170
	global_load_dwordx4 v[18:21], v[170:171], off
	global_load_dwordx4 v[22:25], v[36:37], off
	global_load_dwordx4 v[26:29], v[38:39], off
	v_addc_co_u32_e32 v41, vcc, 0, v171, vcc
	global_load_dwordx4 v[30:33], v[40:41], off
	global_load_dwordx4 v[130:133], v[162:163], off offset:128
	global_load_dwordx4 v[134:137], v[164:165], off offset:128
	global_load_dwordx4 v[138:141], v[166:167], off offset:128
	global_load_dwordx4 v[142:145], v[168:169], off offset:128
	global_load_dwordx4 v[146:149], v[170:171], off offset:128
	global_load_dwordx4 v[150:153], v[36:37], off offset:128
	global_load_dwordx4 v[154:157], v[38:39], off offset:128
	global_load_dwordx4 v[158:161], v[40:41], off offset:128
	v_lshrrev_b32_e32 v35, 4, v42
	v_and_b32_e32 v0, 15, v42
	v_lshrrev_b32_e32 v46, 1, v42
	v_bfe_u32 v47, v42, 1, 3
	v_lshlrev_b32_e32 v48, 1, v42
	v_xor_b32_e32 v42, v35, v42
	v_lshlrev_b32_e32 v42, 3, v42
	s_movk_i32 s5, 0x80
	v_and_b32_e32 v42, 56, v42
	v_bitop3_b32 v35, v35, v47, 3 bitop3:0x6c
	v_and_or_b32 v47, v48, s5, v0
	v_lshlrev_b32_e32 v48, 6, v34
	v_lshlrev_b32_e32 v34, 7, v34
	v_lshlrev_b32_e32 v178, 1, v42
	v_and_or_b32 v46, v46, s62, v0
	v_lshlrev_b32_e32 v0, 3, v35
	v_lshlrev_b32_e32 v35, 6, v43
	v_lshlrev_b32_e32 v43, 7, v43
	v_add3_u32 v42, 0, v34, v178
	v_add3_u32 v51, 0, v43, v178
	s_waitcnt vmcnt(63) expcnt(7) lgkmcnt(15)
	s_barrier
; template <int BN, bool TRANS = false>
; DEV void gemm256_acc(f32x4 (&acc)[4][BN / 32], const bf16_t* __restrict__ A, int lda, int m_valid,
;                      const bf16_t* __restrict__ Bt, int ldb, int K, bf16_t* lds) {
;     ...
;   LSTORE(0)
;   GLOAD(64)
;   __syncthreads();
;   for (int kt = 0; kt < nk; kt++) {
;     const int cur = kt & 1;
;     gemm256_kstep<BN, TRANS>(acc, As + cur * A_SZ + aoff, Bs + cur * B_SZ + boff, sw0);
; DEV void phase_G(const Params& p, int b, unsigned char* ldsraw) {
;     ...
;     f32x4 acc[4][8];
; #pragma unroll
;     for (int i = 0; i < 4; i++)
; #pragma unroll
;       for (int j = 0; j < 8; j++) acc[i][j] = (f32x4){0.f, 0.f, 0.f, 0.f};
	s_mov_b64 s[10:11], 0x40000
	v_lshlrev_b32_e32 v49, 6, v44
	v_xor_b32_e32 v50, 32, v0
	v_lshl_add_u64 v[174:175], v[170:171], 0, s[10:11]
	s_mov_b64 s[10:11], 0x60000
	s_mov_b32 s3, 0
	v_lshl_add_u64 v[172:173], v[170:171], 0, s[84:85]
	v_lshl_add_u64 v[176:177], v[170:171], 0, s[10:11]
	v_lshl_add_u32 v179, v46, 7, 0
	v_lshl_add_u32 v182, v47, 7, s66
	v_lshlrev_b32_e32 v183, 1, v48
	v_lshlrev_b32_e32 v184, 1, v35
	v_lshlrev_b32_e32 v185, 1, v49
	v_lshlrev_b32_e32 v187, 1, v50
	s_mov_b32 s5, 0
	s_waitcnt vmcnt(15)
	ds_write_b128 v42, v[2:5]
	s_waitcnt vmcnt(14)
	ds_write_b128 v51, v[6:9]
	v_lshlrev_b32_e32 v4, 7, v45
	v_lshlrev_b32_e32 v2, 7, v44
	v_add3_u32 v5, 0, v4, v178
	v_add3_u32 v3, 0, v2, v178
	s_waitcnt vmcnt(12)
	ds_write_b128 v5, v[14:17]
	v_add3_u32 v5, s66, v34, v178
	v_add3_u32 v2, s66, v2, v178
	s_waitcnt vmcnt(11)
	ds_write_b128 v5, v[18:21]
	v_add3_u32 v5, s66, v43, v178
	s_waitcnt vmcnt(9)
	ds_write_b128 v2, v[26:29]
	v_add3_u32 v2, s66, v4, v178
	ds_write_b128 v3, v[10:13]
	ds_write_b128 v5, v[22:25]
	s_waitcnt vmcnt(8)
	ds_write_b128 v2, v[30:33]
	v_lshlrev_b32_e32 v3, 6, v45
	v_mov_b32_e32 v2, 0
	v_lshlrev_b32_e32 v186, 1, v3
	v_mov_b32_e32 v3, v2
	v_mov_b32_e32 v4, v2
	v_mov_b32_e32 v5, v2
	v_mov_b32_e32 v6, v2
	v_mov_b32_e32 v7, v2
	v_mov_b32_e32 v8, v2
	v_mov_b32_e32 v9, v2
	v_mov_b32_e32 v10, v2
	v_mov_b32_e32 v11, v2
	v_mov_b32_e32 v12, v2
	v_mov_b32_e32 v13, v2
	v_mov_b32_e32 v14, v2
	v_mov_b32_e32 v15, v2
	v_mov_b32_e32 v16, v2
	v_mov_b32_e32 v17, v2
	v_mov_b32_e32 v18, v2
	v_mov_b32_e32 v19, v2
	v_mov_b32_e32 v20, v2
	v_mov_b32_e32 v21, v2
	v_mov_b32_e32 v22, v2
	v_mov_b32_e32 v23, v2
	v_mov_b32_e32 v24, v2
	v_mov_b32_e32 v25, v2
	v_mov_b32_e32 v26, v2
	v_mov_b32_e32 v27, v2
	v_mov_b32_e32 v28, v2
	v_mov_b32_e32 v29, v2
	v_mov_b32_e32 v30, v2
	v_mov_b32_e32 v31, v2
	v_mov_b32_e32 v32, v2
	v_mov_b32_e32 v33, v2
	v_mov_b32_e32 v34, v2
	v_mov_b32_e32 v35, v2
	v_mov_b32_e32 v36, v2
	v_mov_b32_e32 v37, v2
	v_mov_b32_e32 v38, v2
	v_mov_b32_e32 v39, v2
	v_mov_b32_e32 v40, v2
	v_mov_b32_e32 v41, v2
	v_mov_b32_e32 v42, v2
	v_mov_b32_e32 v43, v2
	v_mov_b32_e32 v44, v2
	v_mov_b32_e32 v45, v2
	v_mov_b32_e32 v46, v2
	v_mov_b32_e32 v47, v2
	v_mov_b32_e32 v48, v2
	v_mov_b32_e32 v49, v2
	v_mov_b32_e32 v50, v2
	v_mov_b32_e32 v51, v2
	v_mov_b32_e32 v52, v2
	v_mov_b32_e32 v53, v2
	v_mov_b32_e32 v54, v2
	v_mov_b32_e32 v55, v2
	v_mov_b32_e32 v56, v2
	v_mov_b32_e32 v57, v2
	v_mov_b32_e32 v58, v2
	v_mov_b32_e32 v59, v2
	v_mov_b32_e32 v60, v2
	v_mov_b32_e32 v61, v2
	v_mov_b32_e32 v62, v2
	v_mov_b32_e32 v63, v2
	v_mov_b32_e32 v64, v2
	v_mov_b32_e32 v65, v2
	v_mov_b32_e32 v66, v2
	v_mov_b32_e32 v67, v2
	v_mov_b32_e32 v68, v2
	v_mov_b32_e32 v69, v2
	v_mov_b32_e32 v70, v2
	v_mov_b32_e32 v71, v2
	v_mov_b32_e32 v72, v2
	v_mov_b32_e32 v73, v2
	v_mov_b32_e32 v74, v2
	v_mov_b32_e32 v75, v2
	v_mov_b32_e32 v76, v2
	v_mov_b32_e32 v77, v2
	v_mov_b32_e32 v78, v2
	v_mov_b32_e32 v79, v2
	v_mov_b32_e32 v80, v2
	v_mov_b32_e32 v81, v2
	v_mov_b32_e32 v82, v2
	v_mov_b32_e32 v83, v2
	v_mov_b32_e32 v84, v2
	v_mov_b32_e32 v85, v2
	v_mov_b32_e32 v86, v2
	v_mov_b32_e32 v87, v2
	v_mov_b32_e32 v88, v2
	v_mov_b32_e32 v89, v2
	v_mov_b32_e32 v90, v2
	v_mov_b32_e32 v91, v2
	v_mov_b32_e32 v92, v2
	v_mov_b32_e32 v93, v2
	v_mov_b32_e32 v94, v2
	v_mov_b32_e32 v95, v2
	v_mov_b32_e32 v96, v2
	v_mov_b32_e32 v97, v2
	v_mov_b32_e32 v98, v2
	v_mov_b32_e32 v99, v2
	v_mov_b32_e32 v100, v2
	v_mov_b32_e32 v101, v2
	v_mov_b32_e32 v102, v2
	v_mov_b32_e32 v103, v2
	v_mov_b32_e32 v104, v2
	v_mov_b32_e32 v105, v2
	v_mov_b32_e32 v106, v2
	v_mov_b32_e32 v107, v2
	v_mov_b32_e32 v108, v2
	v_mov_b32_e32 v109, v2
	v_mov_b32_e32 v110, v2
	v_mov_b32_e32 v111, v2
	v_mov_b32_e32 v112, v2
	v_mov_b32_e32 v113, v2
	v_mov_b32_e32 v114, v2
	v_mov_b32_e32 v115, v2
	v_mov_b32_e32 v116, v2
	v_mov_b32_e32 v117, v2
	v_mov_b32_e32 v118, v2
	v_mov_b32_e32 v119, v2
	v_mov_b32_e32 v120, v2
	v_mov_b32_e32 v121, v2
	v_mov_b32_e32 v122, v2
	v_mov_b32_e32 v123, v2
	v_mov_b32_e32 v124, v2
	v_mov_b32_e32 v125, v2
	v_mov_b32_e32 v126, v2
	v_mov_b32_e32 v127, v2
	v_mov_b32_e32 v128, v2
	v_mov_b32_e32 v129, v2
	s_waitcnt lgkmcnt(0)
	s_barrier
	v_lshlrev_b32_e32 v211, 1, v0
	v_add_u32_e32 v216, v179, v211
	v_add_u32_e32 v206, v182, v211
	ds_read_b128 v[188:191], v216
	ds_read_b128 v[192:195], v216 offset:2048
	ds_read_b128 v[196:199], v216 offset:4096
	ds_read_b128 v[200:203], v216 offset:6144
	ds_read_b128 v[236:239], v206
	ds_read_b128 v[240:243], v206 offset:2048
	ds_read_b128 v[244:247], v206 offset:4096
	ds_read_b128 v[248:251], v206 offset:6144

; template <int BN, bool TRANS = false>
; DEV void gemm256_acc(f32x4 (&acc)[4][BN / 32], const bf16_t* __restrict__ A, int lda, int m_valid,
;                      const bf16_t* __restrict__ Bt, int ldb, int K, bf16_t* lds) {
;     ...
;   const bf16_t* ga0 = A + (size_t)min(crow, m_valid - 1) * lda + ckc;
;   const bf16_t* ga1 = A + (size_t)min(crow + 64, m_valid - 1) * lda + ckc;
;   const bf16_t* ga2 = A + (size_t)min(crow + 128, m_valid - 1) * lda + ckc;
;   const bf16_t* ga3 = A + (size_t)min(crow + 192, m_valid - 1) * lda + ckc;
;   const bf16_t* gb = Bt + (size_t)crow * ldb + ckc;
;   u32x4 ra0, ra1, ra2, ra3, rb0, rb1, rb2, rb3;
;     ...
;   const int nk = K / 64;
;   const int aoff = (wm * 64 + lr) * LS;
;   const int boff = (wn * (BN / 2) + lr) * LS;
;   GLOAD(0)
;   __syncthreads();
;   LSTORE(0)
;   GLOAD(64)
;   __syncthreads();
.LBB0_1045:
	s_cmpk_lt_i32 s2, 0x100
	s_mov_b64 s[0:1], -1
	s_cbranch_scc0 .LBB0_1049
	s_ashr_i32 s0, s2, 31
	s_lshr_b32 s0, s0, 25
	s_add_i32 s0, s2, s0
	s_ashr_i32 s1, s0, 7
	s_and_b32 s0, s0, 0xffffff80
	s_sub_i32 s0, s2, s0
	s_ashr_i32 s4, s0, 31
	s_lshr_b32 s4, s4, 30
	s_add_i32 s4, s0, s4
	s_ashr_i32 s4, s4, 2
	s_sub_i32 s1, s1, s4
	s_lshl_b32 s4, s4, 8
	s_bitset1_b32 s4, 7
	v_mov_b32_e32 v30, v181
	s_lshl_b32 s1, s1, 2
	s_ashr_i32 s5, s4, 31
	s_add_i32 s0, s1, s0
	v_ashrrev_i32_e32 v26, 3, v30
	s_lshl_b64 s[10:11], s[4:5], 11
	v_min_i32_e32 v2, 0xff, v26
	s_add_u32 s10, s90, s10
	v_ashrrev_i32_e32 v3, 31, v2
	s_addc_u32 s11, s91, s11
	v_lshlrev_b64 v[2:3], 11, v[2:3]
	v_lshlrev_b32_e32 v0, 4, v30
	v_lshl_add_u64 v[2:3], s[10:11], 0, v[2:3]
	v_and_b32_e32 v0, 0x70, v0
	v_add_u32_e32 v31, 64, v26
	v_lshl_add_u64 v[90:91], v[2:3], 0, v[0:1]
	v_min_i32_e32 v2, 0xff, v31
	v_ashrrev_i32_e32 v3, 31, v2
	v_lshlrev_b64 v[2:3], 11, v[2:3]
	v_lshl_add_u64 v[2:3], s[10:11], 0, v[2:3]
	v_add_u32_e32 v32, 0x80, v26
	v_lshl_add_u64 v[92:93], v[2:3], 0, v[0:1]
	v_min_i32_e32 v2, 0xff, v32
	v_ashrrev_i32_e32 v3, 31, v2
	v_lshlrev_b64 v[2:3], 11, v[2:3]
	v_lshl_add_u64 v[2:3], s[10:11], 0, v[2:3]
	v_add_u32_e32 v33, 0xc0, v26
	v_lshl_add_u64 v[94:95], v[2:3], 0, v[0:1]
	v_min_i32_e32 v2, 0xff, v33
	s_ashr_i32 s1, s0, 31
	v_ashrrev_i32_e32 v3, 31, v2
	s_lshl_b64 s[12:13], s[0:1], 18
	v_lshlrev_b64 v[2:3], 11, v[2:3]
	s_add_u32 s12, s14, s12
	v_lshl_add_u64 v[2:3], s[10:11], 0, v[2:3]
	v_ashrrev_i32_e32 v27, 31, v26
	s_addc_u32 s13, s15, s13
	v_lshl_add_u64 v[96:97], v[2:3], 0, v[0:1]
	v_lshlrev_b64 v[2:3], 11, v[26:27]
	v_lshl_add_u64 v[2:3], s[12:13], 0, v[2:3]
	v_lshl_add_u64 v[98:99], v[2:3], 0, v[0:1]
	global_load_dwordx4 v[2:5], v[90:91], off
	global_load_dwordx4 v[6:9], v[92:93], off
	global_load_dwordx4 v[10:13], v[94:95], off
	global_load_dwordx4 v[14:17], v[96:97], off
	global_load_dwordx4 v[18:21], v[98:99], off
	v_lshrrev_b32_e32 v0, 4, v30
	v_xor_b32_e32 v35, v0, v30
	v_lshlrev_b32_e32 v35, 3, v35
	v_bfe_u32 v34, v30, 1, 3
	v_and_b32_e32 v35, 56, v35
	v_add_co_u32_e32 v28, vcc, s63, v98
	v_bitop3_b32 v0, v0, v34, 3 bitop3:0x6c
	v_lshlrev_b32_e32 v34, 6, v26
	v_lshlrev_b32_e32 v26, 7, v26
	v_lshlrev_b32_e32 v102, 1, v35
	v_addc_co_u32_e32 v29, vcc, 0, v99, vcc
	v_lshlrev_b32_e32 v36, 6, v31
	v_lshlrev_b32_e32 v31, 7, v31
	v_lshlrev_b32_e32 v37, 6, v32
	v_lshlrev_b32_e32 v32, 7, v32
	v_lshlrev_b32_e32 v58, 6, v33
	v_lshlrev_b32_e32 v33, 7, v33
	v_add3_u32 v35, 0, v26, v102
	global_load_dwordx4 v[22:25], v[28:29], off
	global_load_dwordx4 v[38:41], v[90:91], off offset:128
	global_load_dwordx4 v[42:45], v[92:93], off offset:128
	global_load_dwordx4 v[46:49], v[94:95], off offset:128
	global_load_dwordx4 v[50:53], v[96:97], off offset:128
	global_load_dwordx4 v[54:57], v[98:99], off offset:128
	global_load_dwordx4 v[70:73], v[28:29], off offset:128
	v_add3_u32 v252, 0, v31, v102
	v_add3_u32 v32, 0, v32, v102
	v_add3_u32 v33, 0, v33, v102
	v_add3_u32 v26, s66, v26, v102
	s_waitcnt vmcnt(63) expcnt(7) lgkmcnt(15)
	s_barrier
	v_lshrrev_b32_e32 v27, 1, v30
	v_lshlrev_b32_e32 v0, 3, v0
	v_xor_b32_e32 v59, 32, v0
	v_add3_u32 v31, s66, v31, v102
	s_mov_b32 s1, 0
	v_lshl_add_u64 v[100:101], v[98:99], 0, s[84:85]
	v_lshlrev_b32_e32 v105, 1, v34
	v_lshlrev_b32_e32 v106, 1, v36
	v_lshlrev_b32_e32 v107, 1, v37
	v_lshlrev_b32_e32 v108, 1, v58
	v_lshlrev_b32_e32 v109, 1, v59
	s_waitcnt vmcnt(11)
	ds_write_b128 v35, v[2:5]
	s_waitcnt vmcnt(10)
	ds_write_b128 v252, v[6:9]
	s_waitcnt vmcnt(9)
	ds_write_b128 v32, v[10:13]
	s_waitcnt vmcnt(8)
	ds_write_b128 v33, v[14:17]
	s_waitcnt vmcnt(7)
	ds_write_b128 v26, v[18:21]
	v_lshlrev_b32_e32 v2, 7, v30
	v_and_b32_e32 v2, 0x2780, v2
	v_add_u32_e32 v103, s66, v2
	v_and_b32_e32 v2, 15, v30
	v_and_or_b32 v2, v27, s62, v2
	v_lshl_add_u32 v104, v2, 7, 0
	v_mov_b32_e32 v2, 0
	v_mov_b32_e32 v3, v2
	v_mov_b32_e32 v4, v2
	v_mov_b32_e32 v5, v2
	v_mov_b32_e32 v6, v2
	v_mov_b32_e32 v7, v2
	v_mov_b32_e32 v8, v2
	v_mov_b32_e32 v9, v2
	v_mov_b32_e32 v10, v2
	v_mov_b32_e32 v11, v2
	v_mov_b32_e32 v12, v2
	v_mov_b32_e32 v13, v2
	v_mov_b32_e32 v14, v2
	s_waitcnt vmcnt(6)
	ds_write_b128 v31, v[22:25]
	v_mov_b32_e32 v15, v2
	v_mov_b32_e32 v16, v2
	v_mov_b32_e32 v17, v2
	v_mov_b32_e32 v18, v2
	v_mov_b32_e32 v19, v2
	v_mov_b32_e32 v20, v2
	v_mov_b32_e32 v21, v2
	v_mov_b32_e32 v22, v2
	v_mov_b32_e32 v23, v2
	v_mov_b32_e32 v24, v2
	v_mov_b32_e32 v25, v2
	v_mov_b32_e32 v26, v2
	v_mov_b32_e32 v27, v2
	v_mov_b32_e32 v28, v2
	v_mov_b32_e32 v29, v2
	v_mov_b32_e32 v30, v2
	v_mov_b32_e32 v31, v2
	v_mov_b32_e32 v32, v2
	v_mov_b32_e32 v33, v2
	v_mov_b32_e32 v34, v2
	v_mov_b32_e32 v35, v2
	v_mov_b32_e32 v36, v2
	v_mov_b32_e32 v37, v2
	v_mov_b32_e32 v58, v2
	v_mov_b32_e32 v59, v2
	v_mov_b32_e32 v60, v2
	v_mov_b32_e32 v61, v2
	v_mov_b32_e32 v62, v2
	v_mov_b32_e32 v63, v2
	v_mov_b32_e32 v64, v2
	v_mov_b32_e32 v65, v2
	v_mov_b32_e32 v66, v2
	v_mov_b32_e32 v67, v2
	v_mov_b32_e32 v68, v2
	v_mov_b32_e32 v69, v2
	v_mov_b32_e32 v74, v2
	v_mov_b32_e32 v75, v2
	v_mov_b32_e32 v76, v2
	v_mov_b32_e32 v77, v2
	v_mov_b32_e32 v78, v2
	v_mov_b32_e32 v79, v2
	v_mov_b32_e32 v80, v2
	v_mov_b32_e32 v81, v2
	v_mov_b32_e32 v82, v2
	v_mov_b32_e32 v83, v2
	v_mov_b32_e32 v84, v2
	v_mov_b32_e32 v85, v2
	v_mov_b32_e32 v86, v2
	v_mov_b32_e32 v87, v2
	v_mov_b32_e32 v88, v2
	v_mov_b32_e32 v89, v2
	s_waitcnt lgkmcnt(0)
	s_barrier
	v_lshlrev_b32_e32 v203, 1, v0
	v_add_u32_e32 v216, v104, v203
	v_add_u32_e32 v206, v103, v203
	ds_read_b128 v[110:113], v216
	ds_read_b128 v[114:117], v216 offset:2048
	ds_read_b128 v[118:121], v216 offset:4096
	ds_read_b128 v[122:125], v216 offset:6144
	ds_read_b128 v[236:239], v206
	ds_read_b128 v[240:243], v206 offset:2048
	ds_read_b128 v[244:247], v206 offset:4096
	ds_read_b128 v[248:251], v206 offset:6144

; template <int BN, bool TRANS = false>
; DEV void gemm256_acc(f32x4 (&acc)[4][BN / 32], const bf16_t* __restrict__ A, int lda, int m_valid,
;                      const bf16_t* __restrict__ Bt, int ldb, int K, bf16_t* lds) {
;     ...
;   const bf16_t* ga0 = A + (size_t)min(crow, m_valid - 1) * lda + ckc;
;   const bf16_t* ga1 = A + (size_t)min(crow + 64, m_valid - 1) * lda + ckc;
;   const bf16_t* ga2 = A + (size_t)min(crow + 128, m_valid - 1) * lda + ckc;
;   const bf16_t* ga3 = A + (size_t)min(crow + 192, m_valid - 1) * lda + ckc;
;   const bf16_t* gb = Bt + (size_t)crow * ldb + ckc;
;   u32x4 ra0, ra1, ra2, ra3, rb0, rb1, rb2, rb3;
;     ...
;   const int nk = K / 64;
;   const int aoff = (wm * 64 + lr) * LS;
;   const int boff = (wn * (BN / 2) + lr) * LS;
;   GLOAD(0)
;   __syncthreads();
;   LSTORE(0)
;   GLOAD(64)
;   __syncthreads();
.LBB0_1288:
	s_cmpk_lt_i32 s2, 0x100
	s_mov_b64 s[0:1], -1
	s_cbranch_scc0 .LBB0_1292
	s_ashr_i32 s0, s2, 31
	s_lshr_b32 s0, s0, 25
	s_add_i32 s0, s2, s0
	s_ashr_i32 s1, s0, 7
	s_and_b32 s0, s0, 0xffffff80
	s_sub_i32 s0, s2, s0
	s_ashr_i32 s7, s0, 31
	s_lshr_b32 s7, s7, 30
	s_add_i32 s7, s0, s7
	s_ashr_i32 s7, s7, 2
	s_sub_i32 s1, s1, s7
	s_lshl_b32 s1, s1, 2
	s_lshl_b32 s7, s7, 8
	s_add_i32 s0, s1, s0
	s_or_b32 s1, s7, 0x80
	s_mul_i32 s8, s1, 0x1600
	v_readlane_b32 s10, v254, 59
	s_mul_hi_i32 s7, s1, 0x1600
	v_readlane_b32 s11, v254, 60
	s_add_u32 s8, s10, s8
	s_addc_u32 s9, s11, s7
	s_mul_i32 s10, s0, 0xb0000
	v_mov_b32_e32 v28, v181
	s_mul_hi_i32 s7, s0, 0xb0000
	s_add_u32 s10, s12, s10
	s_addc_u32 s11, s13, s7
	v_ashrrev_i32_e32 v29, 3, v28
	v_min_i32_e32 v0, 0xff, v29
	v_mov_b64_e32 v[2:3], s[8:9]
	s_movk_i32 s7, 0x1600
	v_mad_i64_i32 v[4:5], s[8:9], v0, s7, v[2:3]
	v_lshlrev_b32_e32 v0, 4, v28
	v_and_b32_e32 v0, 0x70, v0
	s_waitcnt vmcnt(3)
	v_add_u32_e32 v30, 64, v29
	v_lshl_add_u64 v[90:91], v[4:5], 0, v[0:1]
	v_min_i32_e32 v4, 0xff, v30
	v_mad_i64_i32 v[4:5], s[8:9], v4, s7, v[2:3]
	v_add_u32_e32 v31, 0x80, v29
	v_lshl_add_u64 v[92:93], v[4:5], 0, v[0:1]
	v_min_i32_e32 v4, 0xff, v31
	v_mad_i64_i32 v[4:5], s[8:9], v4, s7, v[2:3]
	v_add_u32_e32 v32, 0xc0, v29
	v_lshl_add_u64 v[94:95], v[4:5], 0, v[0:1]
	v_min_i32_e32 v4, 0xff, v32
	v_mad_i64_i32 v[2:3], s[8:9], v4, s7, v[2:3]
	v_lshl_add_u64 v[96:97], v[2:3], 0, v[0:1]
	v_mov_b64_e32 v[2:3], s[10:11]
	v_mad_i64_i32 v[2:3], s[8:9], v29, s7, v[2:3]
	v_lshl_add_u64 v[98:99], v[2:3], 0, v[0:1]
	global_load_dwordx4 v[2:5], v[90:91], off
	global_load_dwordx4 v[6:9], v[92:93], off
	global_load_dwordx4 v[10:13], v[94:95], off
	global_load_dwordx4 v[14:17], v[96:97], off
	global_load_dwordx4 v[18:21], v[98:99], off
	v_lshrrev_b32_e32 v0, 4, v28
	v_xor_b32_e32 v35, v0, v28
	s_mov_b32 s7, 0x58000
	v_lshlrev_b32_e32 v35, 3, v35
	v_add_co_u32_e32 v26, vcc, s7, v98
	v_bfe_u32 v34, v28, 1, 3
	v_and_b32_e32 v35, 56, v35
	v_addc_co_u32_e32 v27, vcc, 0, v99, vcc
	v_bitop3_b32 v0, v0, v34, 3 bitop3:0x6c
	v_lshlrev_b32_e32 v34, 6, v29
	v_lshlrev_b32_e32 v29, 7, v29
	v_lshlrev_b32_e32 v102, 1, v35
	global_load_dwordx4 v[22:25], v[26:27], off
	global_load_dwordx4 v[38:41], v[90:91], off offset:128
	global_load_dwordx4 v[42:45], v[92:93], off offset:128
	global_load_dwordx4 v[46:49], v[94:95], off offset:128
	global_load_dwordx4 v[50:53], v[96:97], off offset:128
	global_load_dwordx4 v[54:57], v[98:99], off offset:128
	global_load_dwordx4 v[70:73], v[26:27], off offset:128
	v_lshlrev_b32_e32 v36, 6, v30
	v_lshlrev_b32_e32 v30, 7, v30
	v_lshlrev_b32_e32 v37, 6, v31
	v_lshlrev_b32_e32 v31, 7, v31
	v_lshlrev_b32_e32 v58, 6, v32
	v_lshlrev_b32_e32 v32, 7, v32
	v_add3_u32 v35, 0, v29, v102
	s_barrier
	v_add3_u32 v252, 0, v30, v102
	v_add3_u32 v31, 0, v31, v102
	v_add3_u32 v32, 0, v32, v102
	v_add3_u32 v29, s66, v29, v102
	v_lshrrev_b32_e32 v33, 1, v28
	v_lshlrev_b32_e32 v0, 3, v0
	v_xor_b32_e32 v59, 32, v0
	v_add3_u32 v30, s66, v30, v102
	s_mov_b64 s[8:9], 0x58000
	s_mov_b32 s7, 0
	v_lshl_add_u64 v[100:101], v[98:99], 0, s[8:9]
	v_lshlrev_b32_e32 v105, 1, v34
	v_lshlrev_b32_e32 v106, 1, v36
	v_lshlrev_b32_e32 v107, 1, v37
	v_lshlrev_b32_e32 v108, 1, v58
	v_lshlrev_b32_e32 v109, 1, v59
	s_waitcnt vmcnt(11)
	ds_write_b128 v35, v[2:5]
	s_waitcnt vmcnt(10)
	ds_write_b128 v252, v[6:9]
	s_waitcnt vmcnt(9)
	ds_write_b128 v31, v[10:13]
	s_waitcnt vmcnt(8)
	ds_write_b128 v32, v[14:17]
	s_waitcnt vmcnt(7)
	ds_write_b128 v29, v[18:21]
	v_lshlrev_b32_e32 v2, 7, v28
	v_and_b32_e32 v2, 0x2780, v2
	v_add_u32_e32 v103, s66, v2
	v_and_b32_e32 v2, 15, v28
	v_and_or_b32 v2, v33, s62, v2
	v_lshl_add_u32 v104, v2, 7, 0
	v_mov_b32_e32 v2, 0
	v_mov_b32_e32 v3, v2
	v_mov_b32_e32 v4, v2
	v_mov_b32_e32 v5, v2
	v_mov_b32_e32 v6, v2
	v_mov_b32_e32 v7, v2
	v_mov_b32_e32 v8, v2
	s_waitcnt vmcnt(6)
	ds_write_b128 v30, v[22:25]
	v_mov_b32_e32 v9, v2
	v_mov_b32_e32 v10, v2
	v_mov_b32_e32 v11, v2
	v_mov_b32_e32 v12, v2
	v_mov_b32_e32 v13, v2
	v_mov_b32_e32 v14, v2
	v_mov_b32_e32 v15, v2
	v_mov_b32_e32 v16, v2
	v_mov_b32_e32 v17, v2
	v_mov_b32_e32 v18, v2
	v_mov_b32_e32 v19, v2
	v_mov_b32_e32 v20, v2
	v_mov_b32_e32 v21, v2
	v_mov_b32_e32 v22, v2
	v_mov_b32_e32 v23, v2
	v_mov_b32_e32 v24, v2
	v_mov_b32_e32 v25, v2
	v_mov_b32_e32 v26, v2
	v_mov_b32_e32 v27, v2
	v_mov_b32_e32 v28, v2
	v_mov_b32_e32 v29, v2
	v_mov_b32_e32 v30, v2
	v_mov_b32_e32 v31, v2
	v_mov_b32_e32 v32, v2
	v_mov_b32_e32 v33, v2
	v_mov_b32_e32 v34, v2
	v_mov_b32_e32 v35, v2
	v_mov_b32_e32 v36, v2
	v_mov_b32_e32 v37, v2
	v_mov_b32_e32 v58, v2
	v_mov_b32_e32 v59, v2
	v_mov_b32_e32 v60, v2
	v_mov_b32_e32 v61, v2
	v_mov_b32_e32 v62, v2
	v_mov_b32_e32 v63, v2
	v_mov_b32_e32 v64, v2
	v_mov_b32_e32 v65, v2
	v_mov_b32_e32 v66, v2
	v_mov_b32_e32 v67, v2
	v_mov_b32_e32 v68, v2
	v_mov_b32_e32 v69, v2
	v_mov_b32_e32 v74, v2
	v_mov_b32_e32 v75, v2
	v_mov_b32_e32 v76, v2
	v_mov_b32_e32 v77, v2
	v_mov_b32_e32 v78, v2
	v_mov_b32_e32 v79, v2
	v_mov_b32_e32 v80, v2
	v_mov_b32_e32 v81, v2
	v_mov_b32_e32 v82, v2
	v_mov_b32_e32 v83, v2
	v_mov_b32_e32 v84, v2
	v_mov_b32_e32 v85, v2
	v_mov_b32_e32 v86, v2
	v_mov_b32_e32 v87, v2
	v_mov_b32_e32 v88, v2
	v_mov_b32_e32 v89, v2
	s_waitcnt lgkmcnt(0)
	s_barrier
	v_lshlrev_b32_e32 v203, 1, v0
	v_add_u32_e32 v216, v104, v203
	v_add_u32_e32 v206, v103, v203
	ds_read_b128 v[110:113], v216
	ds_read_b128 v[114:117], v216 offset:2048
	ds_read_b128 v[118:121], v216 offset:4096
	ds_read_b128 v[122:125], v216 offset:6144
	ds_read_b128 v[236:239], v206
	ds_read_b128 v[240:243], v206 offset:2048
	ds_read_b128 v[244:247], v206 offset:4096
	ds_read_b128 v[248:251], v206 offset:6144
